# cv7 + G1/G5 epilogue-start vmcnt(0) relaxed to vmcnt(8) (pre loads are older than the last 8 DMA ops)
# baseline (speedup 1.0000x reference)
.LBB0_309:
	s_lshl_b32 s14, s8, 8
	v_add_u32_e32 v174, s14, v17
	s_cmp_gt_i32 s34, 7
	s_mov_b64 s[8:9], -1
	s_mov_b32 s71, 0x200000
	s_cbranch_scc0 .LBB0_347
	s_cmp_lt_u32 s34, 28
	s_cbranch_scc0 .LBB0_344
	s_cmp_gt_u32 s34, 19
	s_cselect_b64 s[8:9], -1, 0
	s_cmp_lt_u32 s34, 20
	s_waitcnt vmcnt(8)
	v_pk_mul_f32 v[162:163], v[158:159], v[134:135] op_sel_hi:[0,1]
	v_pk_mul_f32 v[166:167], v[158:159], v[132:133] op_sel_hi:[0,1]
	v_pk_mul_f32 v[164:165], v[158:159], v[130:131] op_sel_hi:[0,1]
	v_pk_mul_f32 v[168:169], v[158:159], v[128:129] op_sel_hi:[0,1]
	s_cbranch_scc1 .LBB0_313
	v_mul_f32_e32 v145, 0x3d372713, v166
	v_mul_f32_e32 v34, 0x3fcc422a, v166
	v_fma_f32 v145, v166, v145, 1.0
	v_mul_f32_e32 v34, v34, v145
	v_mul_f32_e32 v34, 0xbfb8aa3b, v34
	v_exp_f32_e32 v34, v34
	v_mul_f32_e32 v145, 0x3d372713, v168
	v_fma_f32 v145, v168, v145, 1.0
	v_add_f32_e32 v34, 1.0, v34
	v_rcp_f32_e32 v160, v34
	v_mul_f32_e32 v34, 0x3fcc422a, v168
	v_mul_f32_e32 v34, v34, v145
	v_mul_f32_e32 v34, 0xbfb8aa3b, v34
	v_exp_f32_e32 v34, v34
	v_mul_f32_e32 v145, 0x3d372713, v167
	v_fma_f32 v145, v167, v145, 1.0
	v_add_f32_e32 v34, 1.0, v34
	v_rcp_f32_e32 v176, v34
	v_mul_f32_e32 v34, 0x3fcc422a, v167
	v_mul_f32_e32 v34, v34, v145
	v_mul_f32_e32 v34, 0xbfb8aa3b, v34
	v_exp_f32_e32 v34, v34
	v_mul_f32_e32 v145, 0x3d372713, v169
	v_fma_f32 v145, v169, v145, 1.0
	v_add_f32_e32 v34, 1.0, v34
	v_rcp_f32_e32 v161, v34
	v_mul_f32_e32 v34, 0x3fcc422a, v169
	v_mul_f32_e32 v34, v34, v145
	v_mul_f32_e32 v34, 0xbfb8aa3b, v34
	v_exp_f32_e32 v34, v34
	v_mul_f32_e32 v145, 0x3d372713, v162
	v_fma_f32 v145, v162, v145, 1.0
	v_pk_mul_f32 v[166:167], v[166:167], v[160:161]
	v_add_f32_e32 v34, 1.0, v34
	v_rcp_f32_e32 v177, v34
	v_mul_f32_e32 v34, 0x3fcc422a, v162
	v_mul_f32_e32 v34, v34, v145
	v_mul_f32_e32 v34, 0xbfb8aa3b, v34
	v_exp_f32_e32 v34, v34
	v_mul_f32_e32 v145, 0x3d372713, v164
	v_fma_f32 v145, v164, v145, 1.0
	v_pk_mul_f32 v[168:169], v[168:169], v[176:177]
	v_add_f32_e32 v34, 1.0, v34
	v_rcp_f32_e32 v184, v34
	v_mul_f32_e32 v34, 0x3fcc422a, v164
	v_mul_f32_e32 v34, v34, v145
	v_mul_f32_e32 v34, 0xbfb8aa3b, v34
	v_exp_f32_e32 v34, v34
	v_mul_f32_e32 v145, 0x3d372713, v163
	v_fma_f32 v145, v163, v145, 1.0
	v_add_f32_e32 v34, 1.0, v34
	v_rcp_f32_e32 v186, v34
	v_mul_f32_e32 v34, 0x3fcc422a, v163
	v_mul_f32_e32 v34, v34, v145
	v_mul_f32_e32 v34, 0xbfb8aa3b, v34
	v_exp_f32_e32 v34, v34
	v_mul_f32_e32 v145, 0x3d372713, v165
	v_fma_f32 v145, v165, v145, 1.0
	v_add_f32_e32 v34, 1.0, v34
	v_rcp_f32_e32 v185, v34
	v_mul_f32_e32 v34, 0x3fcc422a, v165
	v_mul_f32_e32 v34, v34, v145
	v_mul_f32_e32 v34, 0xbfb8aa3b, v34
	v_exp_f32_e32 v34, v34
	v_pk_mul_f32 v[162:163], v[162:163], v[184:185]
	v_add_f32_e32 v34, 1.0, v34
	v_rcp_f32_e32 v187, v34
	s_nop 0
	v_pk_mul_f32 v[164:165], v[164:165], v[186:187]

.LBB0_344:
	s_and_b64 vcc, exec, s[8:9]
	s_cbranch_vccz .LBB0_346
	s_waitcnt vmcnt(8)
	v_mul_f32_e32 v34, 0xbfb8aa3b, v158
	v_mul_f32_e32 v160, v34, v133
	v_mul_f32_e32 v162, v34, v129
	v_exp_f32_e32 v160, v160
	v_exp_f32_e32 v162, v162
	v_mul_f32_e32 v161, v34, v125
	v_mul_f32_e32 v163, v34, v121
	v_add_f32_e32 v160, 1.0, v160
	v_exp_f32_e32 v161, v161
	v_exp_f32_e32 v163, v163
	v_add_f32_e32 v162, 1.0, v162
	v_mul_f32_e32 v164, v34, v134
	v_rcp_f32_e32 v160, v160
	v_rcp_f32_e32 v162, v162
	v_exp_f32_e32 v164, v164
	v_add_f32_e32 v161, 1.0, v161
	v_add_f32_e32 v163, 1.0, v163
	v_mul_f32_e32 v160, v161, v160
	v_rcp_f32_e32 v166, v161
	v_mul_f32_e32 v162, v163, v162
	v_rcp_f32_e32 v167, v163
	v_add_f32_e32 v161, 1.0, v164
	v_mul_f32_e32 v163, v34, v126
	v_mul_f32_e32 v164, v34, v130
	v_exp_f32_e32 v163, v163
	v_exp_f32_e32 v164, v164
	v_rcp_f32_e32 v161, v161
	v_mul_f32_e32 v165, v34, v122
	v_exp_f32_e32 v165, v165
	v_add_f32_e32 v163, 1.0, v163
	v_add_f32_e32 v164, 1.0, v164
	v_mul_f32_e32 v169, v34, v127
	v_mul_f32_e32 v161, v163, v161
	v_rcp_f32_e32 v168, v163
	v_rcp_f32_e32 v163, v164
	v_exp_f32_e32 v169, v169
	v_add_f32_e32 v165, 1.0, v165
	v_mul_f32_e32 v164, v34, v135
	v_mul_f32_e32 v163, v165, v163
	v_rcp_f32_e32 v175, v165
	v_add_f32_e32 v165, 1.0, v169
	v_mul_f32_e32 v169, v34, v131
	v_mul_f32_e32 v145, v34, v132
	v_mul_f32_e32 v149, v34, v128
	v_exp_f32_e32 v164, v164
	v_exp_f32_e32 v169, v169
	v_exp_f32_e32 v145, v145
	v_exp_f32_e32 v149, v149
	v_mul_f32_e32 v147, v34, v124
	v_mul_f32_e32 v155, v34, v120
	v_mul_f32_e32 v34, v34, v123
	v_add_f32_e32 v164, 1.0, v164
	v_exp_f32_e32 v34, v34
	v_add_f32_e32 v169, 1.0, v169
	s_lshl_b32 s8, s34, 4
	v_exp_f32_e32 v147, v147
	v_add_f32_e32 v145, 1.0, v145
	v_exp_f32_e32 v155, v155
	v_add_f32_e32 v149, 1.0, v149
	v_rcp_f32_e32 v164, v164
	v_rcp_f32_e32 v169, v169
	v_rcp_f32_e32 v145, v145
	v_rcp_f32_e32 v149, v149
	s_add_i32 s8, s8, s14
	s_add_i32 s16, s8, 0xfffffe40
	v_add_f32_e32 v34, 1.0, v34
	s_ashr_i32 s17, s16, 31
	v_add_f32_e32 v147, 1.0, v147
	v_add_f32_e32 v155, 1.0, v155
	v_mul_f32_e32 v164, v165, v164
	v_rcp_f32_e32 v176, v165
	v_mul_f32_e32 v165, v34, v169
	s_lshl_b64 s[16:17], s[16:17], 13
	v_mul_f32_e32 v145, v147, v145
	v_mul_f32_e32 v149, v155, v149
	v_cvt_pk_bf16_f32 v160, v145, v160
	v_cvt_pk_bf16_f32 v161, v161, v164
	v_cvt_pk_bf16_f32 v162, v149, v162
	v_cvt_pk_bf16_f32 v163, v163, v165
	v_lshl_add_u64 v[164:165], v[150:151], 0, s[16:17]
	v_rcp_f32_e32 v34, v34
	global_store_dwordx4 v[164:165], v[160:163], off
	v_add_co_u32_e32 v164, vcc, s15, v164
	v_rcp_f32_e32 v147, v147
	v_rcp_f32_e32 v155, v155
	v_cvt_pk_bf16_f32 v160, v147, v166
	v_cvt_pk_bf16_f32 v161, v168, v176
	v_cvt_pk_bf16_f32 v162, v155, v167
	v_cvt_pk_bf16_f32 v163, v175, v34
	v_mul_f32_e32 v34, 0xbfb8aa3b, v159
	v_addc_co_u32_e32 v165, vcc, 0, v165, vcc
	global_store_dwordx4 v[164:165], v[160:163], off
	v_mul_f32_e32 v164, v34, v118
	v_exp_f32_e32 v164, v164
	v_mul_f32_e32 v160, v34, v117
	v_mul_f32_e32 v162, v34, v113
	v_exp_f32_e32 v160, v160
	v_exp_f32_e32 v162, v162
	v_mul_f32_e32 v161, v34, v109
	v_mul_f32_e32 v163, v34, v105
	v_add_f32_e32 v160, 1.0, v160
	v_exp_f32_e32 v161, v161
	v_exp_f32_e32 v163, v163
	v_add_f32_e32 v162, 1.0, v162
	v_rcp_f32_e32 v160, v160
	v_rcp_f32_e32 v162, v162
	v_add_f32_e32 v161, 1.0, v161
	v_add_f32_e32 v163, 1.0, v163
	v_mul_f32_e32 v160, v161, v160
	v_rcp_f32_e32 v166, v161
	v_mul_f32_e32 v162, v163, v162
	v_rcp_f32_e32 v167, v163
	v_add_f32_e32 v161, 1.0, v164
	v_mul_f32_e32 v163, v34, v110
	v_mul_f32_e32 v164, v34, v114
	v_exp_f32_e32 v163, v163
	v_exp_f32_e32 v164, v164
	v_rcp_f32_e32 v161, v161
	v_mul_f32_e32 v165, v34, v106
	v_exp_f32_e32 v165, v165
	v_add_f32_e32 v163, 1.0, v163
	v_add_f32_e32 v164, 1.0, v164
	v_mul_f32_e32 v169, v34, v111
	v_mul_f32_e32 v161, v163, v161
	v_rcp_f32_e32 v168, v163
	v_rcp_f32_e32 v163, v164
	v_exp_f32_e32 v169, v169
	v_add_f32_e32 v165, 1.0, v165
	v_mul_f32_e32 v164, v34, v119
	v_mul_f32_e32 v163, v165, v163
	v_rcp_f32_e32 v175, v165
	v_add_f32_e32 v165, 1.0, v169
	v_mul_f32_e32 v169, v34, v115
	v_mul_f32_e32 v145, v34, v116
	v_mul_f32_e32 v149, v34, v112
	v_exp_f32_e32 v164, v164
	v_exp_f32_e32 v169, v169
	v_exp_f32_e32 v145, v145
	v_exp_f32_e32 v149, v149
	v_mul_f32_e32 v147, v34, v108
	v_mul_f32_e32 v155, v34, v104
	v_mul_f32_e32 v34, v34, v107
	v_add_f32_e32 v164, 1.0, v164
	v_exp_f32_e32 v34, v34
	v_add_f32_e32 v169, 1.0, v169
	v_add_f32_e32 v145, 1.0, v145
	v_exp_f32_e32 v147, v147
	v_exp_f32_e32 v155, v155
	v_add_f32_e32 v149, 1.0, v149
	v_rcp_f32_e32 v164, v164
	v_rcp_f32_e32 v169, v169
	v_rcp_f32_e32 v145, v145
	v_rcp_f32_e32 v149, v149
	s_add_i32 s16, s8, 0xfffffe42
	v_add_f32_e32 v34, 1.0, v34
	s_ashr_i32 s17, s16, 31
	v_add_f32_e32 v147, 1.0, v147
	v_add_f32_e32 v155, 1.0, v155
	v_mul_f32_e32 v164, v165, v164
	v_rcp_f32_e32 v176, v165
	v_mul_f32_e32 v165, v34, v169
	s_lshl_b64 s[16:17], s[16:17], 13
	v_mul_f32_e32 v145, v147, v145
	v_mul_f32_e32 v149, v155, v149
	v_cvt_pk_bf16_f32 v160, v145, v160
	v_cvt_pk_bf16_f32 v161, v161, v164
	v_cvt_pk_bf16_f32 v162, v149, v162
	v_cvt_pk_bf16_f32 v163, v163, v165
	v_lshl_add_u64 v[164:165], v[150:151], 0, s[16:17]
	v_rcp_f32_e32 v34, v34
	global_store_dwordx4 v[164:165], v[160:163], off
	v_add_co_u32_e32 v164, vcc, s15, v164
	v_rcp_f32_e32 v147, v147
	v_rcp_f32_e32 v155, v155
	v_cvt_pk_bf16_f32 v160, v147, v166
	v_cvt_pk_bf16_f32 v161, v168, v176
	v_cvt_pk_bf16_f32 v162, v155, v167
	v_cvt_pk_bf16_f32 v163, v175, v34
	v_mul_f32_e32 v34, 0xbfb8aa3b, v154
	v_addc_co_u32_e32 v165, vcc, 0, v165, vcc
	global_store_dwordx4 v[164:165], v[160:163], off
	v_mul_f32_e32 v164, v34, v102
	v_exp_f32_e32 v164, v164
	v_mul_f32_e32 v160, v34, v101
	v_mul_f32_e32 v162, v34, v97
	v_exp_f32_e32 v160, v160
	v_exp_f32_e32 v162, v162
	v_mul_f32_e32 v161, v34, v93
	v_mul_f32_e32 v163, v34, v89
	v_add_f32_e32 v160, 1.0, v160
	v_exp_f32_e32 v161, v161
	v_exp_f32_e32 v163, v163
	v_add_f32_e32 v162, 1.0, v162
	v_rcp_f32_e32 v160, v160
	v_rcp_f32_e32 v162, v162
	v_add_f32_e32 v161, 1.0, v161
	v_add_f32_e32 v163, 1.0, v163
	v_mul_f32_e32 v160, v161, v160
	v_rcp_f32_e32 v166, v161
	v_mul_f32_e32 v162, v163, v162
	v_rcp_f32_e32 v167, v163
	v_add_f32_e32 v161, 1.0, v164
	v_mul_f32_e32 v163, v34, v94
	v_mul_f32_e32 v164, v34, v98
	v_exp_f32_e32 v163, v163
	v_exp_f32_e32 v164, v164
	v_rcp_f32_e32 v161, v161
	v_mul_f32_e32 v165, v34, v90
	v_exp_f32_e32 v165, v165
	v_add_f32_e32 v163, 1.0, v163
	v_add_f32_e32 v164, 1.0, v164
	v_mul_f32_e32 v169, v34, v95
	v_mul_f32_e32 v161, v163, v161
	v_rcp_f32_e32 v168, v163
	v_rcp_f32_e32 v163, v164
	v_exp_f32_e32 v169, v169
	v_add_f32_e32 v165, 1.0, v165
	v_mul_f32_e32 v164, v34, v103
	v_mul_f32_e32 v163, v165, v163
	v_rcp_f32_e32 v175, v165
	v_add_f32_e32 v165, 1.0, v169
	v_mul_f32_e32 v169, v34, v99
	v_mul_f32_e32 v145, v34, v100
	v_mul_f32_e32 v149, v34, v96
	v_exp_f32_e32 v164, v164
	v_exp_f32_e32 v169, v169
	v_exp_f32_e32 v145, v145
	v_exp_f32_e32 v149, v149
	v_mul_f32_e32 v147, v34, v92
	v_mul_f32_e32 v155, v34, v88
	v_mul_f32_e32 v34, v34, v91
	v_add_f32_e32 v164, 1.0, v164
	v_exp_f32_e32 v34, v34
	v_add_f32_e32 v169, 1.0, v169
	v_add_f32_e32 v145, 1.0, v145
	v_exp_f32_e32 v147, v147
	v_exp_f32_e32 v155, v155
	v_add_f32_e32 v149, 1.0, v149
	v_rcp_f32_e32 v164, v164
	v_rcp_f32_e32 v169, v169
	v_rcp_f32_e32 v145, v145
	v_rcp_f32_e32 v149, v149
	s_add_i32 s16, s8, 0xfffffe44
	v_add_f32_e32 v34, 1.0, v34
	s_ashr_i32 s17, s16, 31
	v_add_f32_e32 v147, 1.0, v147
	v_add_f32_e32 v155, 1.0, v155
	v_mul_f32_e32 v164, v165, v164
	v_rcp_f32_e32 v176, v165
	v_mul_f32_e32 v165, v34, v169
	s_lshl_b64 s[16:17], s[16:17], 13
	v_mul_f32_e32 v145, v147, v145
	v_mul_f32_e32 v149, v155, v149
	v_cvt_pk_bf16_f32 v160, v145, v160
	v_cvt_pk_bf16_f32 v161, v161, v164
	v_cvt_pk_bf16_f32 v162, v149, v162
	v_cvt_pk_bf16_f32 v163, v163, v165
	v_lshl_add_u64 v[164:165], v[150:151], 0, s[16:17]
	v_rcp_f32_e32 v34, v34
	global_store_dwordx4 v[164:165], v[160:163], off
	v_add_co_u32_e32 v164, vcc, s15, v164
	v_rcp_f32_e32 v147, v147
	v_rcp_f32_e32 v155, v155
	v_cvt_pk_bf16_f32 v160, v147, v166
	v_cvt_pk_bf16_f32 v161, v168, v176
	v_cvt_pk_bf16_f32 v162, v155, v167
	v_cvt_pk_bf16_f32 v163, v175, v34
	v_mul_f32_e32 v34, 0xbfb8aa3b, v148
	v_addc_co_u32_e32 v165, vcc, 0, v165, vcc
	global_store_dwordx4 v[164:165], v[160:163], off
	v_mul_f32_e32 v164, v34, v86
	v_exp_f32_e32 v164, v164
	v_mul_f32_e32 v160, v34, v85
	v_mul_f32_e32 v162, v34, v81
	v_exp_f32_e32 v160, v160
	v_exp_f32_e32 v162, v162
	v_mul_f32_e32 v161, v34, v77
	v_mul_f32_e32 v163, v34, v73
	v_add_f32_e32 v160, 1.0, v160
	v_exp_f32_e32 v161, v161
	v_exp_f32_e32 v163, v163
	v_add_f32_e32 v162, 1.0, v162
	v_rcp_f32_e32 v160, v160
	v_rcp_f32_e32 v162, v162
	v_add_f32_e32 v161, 1.0, v161
	v_add_f32_e32 v163, 1.0, v163
	v_mul_f32_e32 v160, v161, v160
	v_rcp_f32_e32 v166, v161
	v_mul_f32_e32 v162, v163, v162
	v_rcp_f32_e32 v167, v163
	v_add_f32_e32 v161, 1.0, v164
	v_mul_f32_e32 v163, v34, v78
	v_mul_f32_e32 v164, v34, v82
	v_exp_f32_e32 v163, v163
	v_exp_f32_e32 v164, v164
	v_rcp_f32_e32 v161, v161
	v_mul_f32_e32 v165, v34, v74
	v_exp_f32_e32 v165, v165
	v_add_f32_e32 v163, 1.0, v163
	v_add_f32_e32 v164, 1.0, v164
	v_mul_f32_e32 v169, v34, v79
	v_mul_f32_e32 v161, v163, v161
	v_rcp_f32_e32 v168, v163
	v_rcp_f32_e32 v163, v164
	v_exp_f32_e32 v169, v169
	v_add_f32_e32 v165, 1.0, v165
	v_mul_f32_e32 v164, v34, v87
	v_mul_f32_e32 v163, v165, v163
	v_rcp_f32_e32 v175, v165
	v_add_f32_e32 v165, 1.0, v169
	v_mul_f32_e32 v169, v34, v83
	v_mul_f32_e32 v145, v34, v84
	v_mul_f32_e32 v149, v34, v80
	v_exp_f32_e32 v164, v164
	v_exp_f32_e32 v169, v169
	v_exp_f32_e32 v145, v145
	v_exp_f32_e32 v149, v149
	v_mul_f32_e32 v147, v34, v76
	v_mul_f32_e32 v155, v34, v72
	v_mul_f32_e32 v34, v34, v75
	v_add_f32_e32 v164, 1.0, v164
	v_exp_f32_e32 v34, v34
	v_add_f32_e32 v169, 1.0, v169
	v_add_f32_e32 v145, 1.0, v145
	v_exp_f32_e32 v147, v147
	v_exp_f32_e32 v155, v155
	v_add_f32_e32 v149, 1.0, v149
	v_rcp_f32_e32 v164, v164
	v_rcp_f32_e32 v169, v169
	v_rcp_f32_e32 v145, v145
	v_rcp_f32_e32 v149, v149
	s_add_i32 s16, s8, 0xfffffe46
	v_add_f32_e32 v34, 1.0, v34
	s_ashr_i32 s17, s16, 31
	v_add_f32_e32 v147, 1.0, v147
	v_add_f32_e32 v155, 1.0, v155
	v_mul_f32_e32 v164, v165, v164
	v_rcp_f32_e32 v176, v165
	v_mul_f32_e32 v165, v34, v169
	s_lshl_b64 s[16:17], s[16:17], 13
	v_mul_f32_e32 v145, v147, v145
	v_mul_f32_e32 v149, v155, v149
	v_cvt_pk_bf16_f32 v160, v145, v160
	v_cvt_pk_bf16_f32 v161, v161, v164
	v_cvt_pk_bf16_f32 v162, v149, v162
	v_cvt_pk_bf16_f32 v163, v163, v165
	v_lshl_add_u64 v[164:165], v[150:151], 0, s[16:17]
	v_rcp_f32_e32 v34, v34
	global_store_dwordx4 v[164:165], v[160:163], off
	v_add_co_u32_e32 v164, vcc, s15, v164
	v_rcp_f32_e32 v147, v147
	v_rcp_f32_e32 v155, v155
	v_cvt_pk_bf16_f32 v160, v147, v166
	v_cvt_pk_bf16_f32 v161, v168, v176
	v_cvt_pk_bf16_f32 v162, v155, v167
	v_cvt_pk_bf16_f32 v163, v175, v34
	v_mul_f32_e32 v34, 0xbfb8aa3b, v146
	v_addc_co_u32_e32 v165, vcc, 0, v165, vcc
	global_store_dwordx4 v[164:165], v[160:163], off
	v_mul_f32_e32 v164, v34, v70
	v_exp_f32_e32 v164, v164
	v_mul_f32_e32 v160, v34, v69
	v_mul_f32_e32 v162, v34, v65
	v_exp_f32_e32 v160, v160
	v_exp_f32_e32 v162, v162
	v_mul_f32_e32 v161, v34, v61
	v_mul_f32_e32 v163, v34, v57
	v_add_f32_e32 v160, 1.0, v160
	v_exp_f32_e32 v161, v161
	v_exp_f32_e32 v163, v163
	v_add_f32_e32 v162, 1.0, v162
	v_rcp_f32_e32 v160, v160
	v_rcp_f32_e32 v162, v162
	v_add_f32_e32 v161, 1.0, v161
	v_add_f32_e32 v163, 1.0, v163
	v_mul_f32_e32 v160, v161, v160
	v_rcp_f32_e32 v166, v161
	v_mul_f32_e32 v162, v163, v162
	v_rcp_f32_e32 v167, v163
	v_add_f32_e32 v161, 1.0, v164
	v_mul_f32_e32 v163, v34, v62
	v_mul_f32_e32 v164, v34, v66
	v_exp_f32_e32 v163, v163
	v_exp_f32_e32 v164, v164
	v_rcp_f32_e32 v161, v161
	v_mul_f32_e32 v165, v34, v58
	v_exp_f32_e32 v165, v165
	v_add_f32_e32 v163, 1.0, v163
	v_add_f32_e32 v164, 1.0, v164
	v_mul_f32_e32 v169, v34, v63
	v_mul_f32_e32 v161, v163, v161
	v_rcp_f32_e32 v168, v163
	v_rcp_f32_e32 v163, v164
	v_exp_f32_e32 v169, v169
	v_add_f32_e32 v165, 1.0, v165
	v_mul_f32_e32 v164, v34, v71
	v_mul_f32_e32 v163, v165, v163
	v_rcp_f32_e32 v175, v165
	v_add_f32_e32 v165, 1.0, v169
	v_mul_f32_e32 v169, v34, v67
	v_mul_f32_e32 v145, v34, v68
	v_mul_f32_e32 v149, v34, v64
	v_exp_f32_e32 v164, v164
	v_exp_f32_e32 v169, v169
	v_exp_f32_e32 v145, v145
	v_exp_f32_e32 v149, v149
	v_mul_f32_e32 v147, v34, v60
	v_mul_f32_e32 v155, v34, v56
	v_mul_f32_e32 v34, v34, v59
	v_add_f32_e32 v164, 1.0, v164
	v_exp_f32_e32 v34, v34
	v_add_f32_e32 v169, 1.0, v169
	v_add_f32_e32 v145, 1.0, v145
	v_exp_f32_e32 v147, v147
	v_exp_f32_e32 v155, v155
	v_add_f32_e32 v149, 1.0, v149
	v_rcp_f32_e32 v164, v164
	v_rcp_f32_e32 v169, v169
	v_rcp_f32_e32 v145, v145
	v_rcp_f32_e32 v149, v149
	s_add_i32 s16, s8, 0xfffffe48
	v_add_f32_e32 v34, 1.0, v34
	s_ashr_i32 s17, s16, 31
	v_add_f32_e32 v147, 1.0, v147
	v_add_f32_e32 v155, 1.0, v155
	v_mul_f32_e32 v164, v165, v164
	v_rcp_f32_e32 v176, v165
	v_mul_f32_e32 v165, v34, v169
	s_lshl_b64 s[16:17], s[16:17], 13
	v_mul_f32_e32 v145, v147, v145
	v_mul_f32_e32 v149, v155, v149
	v_cvt_pk_bf16_f32 v160, v145, v160
	v_cvt_pk_bf16_f32 v161, v161, v164
	v_cvt_pk_bf16_f32 v162, v149, v162
	v_cvt_pk_bf16_f32 v163, v163, v165
	v_lshl_add_u64 v[164:165], v[150:151], 0, s[16:17]
	v_rcp_f32_e32 v34, v34
	global_store_dwordx4 v[164:165], v[160:163], off
	v_add_co_u32_e32 v164, vcc, s15, v164
	v_rcp_f32_e32 v147, v147
	v_rcp_f32_e32 v155, v155
	v_cvt_pk_bf16_f32 v160, v147, v166
	v_cvt_pk_bf16_f32 v161, v168, v176
	v_cvt_pk_bf16_f32 v162, v155, v167
	v_cvt_pk_bf16_f32 v163, v175, v34
	v_mul_f32_e32 v34, 0xbfb8aa3b, v144
	v_addc_co_u32_e32 v165, vcc, 0, v165, vcc
	global_store_dwordx4 v[164:165], v[160:163], off
	v_mul_f32_e32 v164, v34, v54
	v_exp_f32_e32 v164, v164
	v_mul_f32_e32 v160, v34, v53
	v_mul_f32_e32 v162, v34, v49
	v_exp_f32_e32 v160, v160
	v_exp_f32_e32 v162, v162
	v_mul_f32_e32 v161, v34, v45
	v_mul_f32_e32 v163, v34, v41
	v_add_f32_e32 v160, 1.0, v160
	v_exp_f32_e32 v161, v161
	v_exp_f32_e32 v163, v163
	v_add_f32_e32 v162, 1.0, v162
	v_rcp_f32_e32 v160, v160
	v_rcp_f32_e32 v162, v162
	v_add_f32_e32 v161, 1.0, v161
	v_add_f32_e32 v163, 1.0, v163
	v_mul_f32_e32 v160, v161, v160
	v_rcp_f32_e32 v166, v161
	v_mul_f32_e32 v162, v163, v162
	v_rcp_f32_e32 v167, v163
	v_add_f32_e32 v161, 1.0, v164
	v_mul_f32_e32 v163, v34, v46
	v_mul_f32_e32 v164, v34, v50
	v_exp_f32_e32 v163, v163
	v_exp_f32_e32 v164, v164
	v_rcp_f32_e32 v161, v161
	v_mul_f32_e32 v165, v34, v42
	v_exp_f32_e32 v165, v165
	v_add_f32_e32 v163, 1.0, v163
	v_add_f32_e32 v164, 1.0, v164
	v_mul_f32_e32 v169, v34, v47
	v_mul_f32_e32 v161, v163, v161
	v_rcp_f32_e32 v168, v163
	v_rcp_f32_e32 v163, v164
	v_exp_f32_e32 v169, v169
	v_add_f32_e32 v165, 1.0, v165
	v_mul_f32_e32 v164, v34, v55
	v_mul_f32_e32 v163, v165, v163
	v_rcp_f32_e32 v175, v165
	v_add_f32_e32 v165, 1.0, v169
	v_mul_f32_e32 v169, v34, v51
	v_mul_f32_e32 v145, v34, v52
	v_mul_f32_e32 v149, v34, v48
	v_exp_f32_e32 v164, v164
	v_exp_f32_e32 v169, v169
	v_exp_f32_e32 v145, v145
	v_exp_f32_e32 v149, v149
	v_mul_f32_e32 v147, v34, v44
	v_mul_f32_e32 v155, v34, v40
	v_mul_f32_e32 v34, v34, v43
	v_add_f32_e32 v164, 1.0, v164
	v_exp_f32_e32 v34, v34
	v_add_f32_e32 v169, 1.0, v169
	v_add_f32_e32 v145, 1.0, v145
	v_exp_f32_e32 v147, v147
	v_exp_f32_e32 v155, v155
	v_add_f32_e32 v149, 1.0, v149
	v_rcp_f32_e32 v164, v164
	v_rcp_f32_e32 v169, v169
	v_rcp_f32_e32 v145, v145
	v_rcp_f32_e32 v149, v149
	s_add_i32 s16, s8, 0xfffffe4a
	v_add_f32_e32 v34, 1.0, v34
	s_ashr_i32 s17, s16, 31
	v_add_f32_e32 v147, 1.0, v147
	v_add_f32_e32 v155, 1.0, v155
	v_mul_f32_e32 v164, v165, v164
	v_rcp_f32_e32 v176, v165
	v_mul_f32_e32 v165, v34, v169
	s_lshl_b64 s[16:17], s[16:17], 13
	v_mul_f32_e32 v145, v147, v145
	v_mul_f32_e32 v149, v155, v149
	v_cvt_pk_bf16_f32 v160, v145, v160
	v_cvt_pk_bf16_f32 v161, v161, v164
	v_cvt_pk_bf16_f32 v162, v149, v162
	v_cvt_pk_bf16_f32 v163, v163, v165
	v_lshl_add_u64 v[164:165], v[150:151], 0, s[16:17]
	v_rcp_f32_e32 v34, v34
	global_store_dwordx4 v[164:165], v[160:163], off
	v_add_co_u32_e32 v164, vcc, s15, v164
	v_rcp_f32_e32 v147, v147
	v_rcp_f32_e32 v155, v155
	v_cvt_pk_bf16_f32 v160, v147, v166
	v_cvt_pk_bf16_f32 v161, v168, v176
	v_cvt_pk_bf16_f32 v162, v155, v167
	v_cvt_pk_bf16_f32 v163, v175, v34
	v_mul_f32_e32 v34, 0xbfb8aa3b, v142
	v_addc_co_u32_e32 v165, vcc, 0, v165, vcc
	global_store_dwordx4 v[164:165], v[160:163], off
	v_mul_f32_e32 v164, v34, v38
	v_exp_f32_e32 v164, v164
	v_mul_f32_e32 v160, v34, v37
	v_mul_f32_e32 v162, v34, v31
	v_exp_f32_e32 v160, v160
	v_exp_f32_e32 v162, v162
	v_mul_f32_e32 v161, v34, v27
	v_mul_f32_e32 v163, v34, v23
	v_add_f32_e32 v160, 1.0, v160
	v_exp_f32_e32 v161, v161
	v_exp_f32_e32 v163, v163
	v_add_f32_e32 v162, 1.0, v162
	v_rcp_f32_e32 v160, v160
	v_rcp_f32_e32 v162, v162
	v_add_f32_e32 v161, 1.0, v161
	v_add_f32_e32 v163, 1.0, v163
	v_mul_f32_e32 v160, v161, v160
	v_rcp_f32_e32 v166, v161
	v_mul_f32_e32 v162, v163, v162
	v_rcp_f32_e32 v167, v163
	v_add_f32_e32 v161, 1.0, v164
	v_mul_f32_e32 v163, v34, v28
	v_mul_f32_e32 v164, v34, v32
	v_exp_f32_e32 v163, v163
	v_exp_f32_e32 v164, v164
	v_rcp_f32_e32 v161, v161
	v_mul_f32_e32 v165, v34, v24
	v_exp_f32_e32 v165, v165
	v_add_f32_e32 v163, 1.0, v163
	v_add_f32_e32 v164, 1.0, v164
	v_mul_f32_e32 v169, v34, v29
	v_mul_f32_e32 v161, v163, v161
	v_rcp_f32_e32 v168, v163
	v_rcp_f32_e32 v163, v164
	v_exp_f32_e32 v169, v169
	v_add_f32_e32 v165, 1.0, v165
	v_mul_f32_e32 v164, v34, v39
	v_mul_f32_e32 v163, v165, v163
	v_rcp_f32_e32 v175, v165
	v_add_f32_e32 v165, 1.0, v169
	v_mul_f32_e32 v169, v34, v33
	v_mul_f32_e32 v145, v34, v36
	v_mul_f32_e32 v149, v34, v30
	v_exp_f32_e32 v164, v164
	v_exp_f32_e32 v169, v169
	v_exp_f32_e32 v145, v145
	v_exp_f32_e32 v149, v149
	v_mul_f32_e32 v147, v34, v26
	v_mul_f32_e32 v155, v34, v22
	v_mul_f32_e32 v34, v34, v25
	v_add_f32_e32 v164, 1.0, v164
	v_exp_f32_e32 v34, v34
	v_add_f32_e32 v169, 1.0, v169
	v_add_f32_e32 v145, 1.0, v145
	v_exp_f32_e32 v147, v147
	v_exp_f32_e32 v155, v155
	v_add_f32_e32 v149, 1.0, v149
	v_rcp_f32_e32 v164, v164
	v_rcp_f32_e32 v169, v169
	v_rcp_f32_e32 v145, v145
	v_rcp_f32_e32 v149, v149
	s_add_i32 s16, s8, 0xfffffe4c
	v_add_f32_e32 v34, 1.0, v34
	s_ashr_i32 s17, s16, 31
	v_add_f32_e32 v147, 1.0, v147
	v_add_f32_e32 v155, 1.0, v155
	v_mul_f32_e32 v164, v165, v164
	v_rcp_f32_e32 v176, v165
	v_mul_f32_e32 v165, v34, v169
	s_lshl_b64 s[16:17], s[16:17], 13
	v_mul_f32_e32 v145, v147, v145
	v_mul_f32_e32 v149, v155, v149
	v_cvt_pk_bf16_f32 v160, v145, v160
	v_cvt_pk_bf16_f32 v161, v161, v164
	v_cvt_pk_bf16_f32 v162, v149, v162
	v_cvt_pk_bf16_f32 v163, v163, v165
	v_lshl_add_u64 v[164:165], v[150:151], 0, s[16:17]
	v_rcp_f32_e32 v34, v34
	global_store_dwordx4 v[164:165], v[160:163], off
	v_add_co_u32_e32 v164, vcc, s15, v164
	v_rcp_f32_e32 v147, v147
	v_rcp_f32_e32 v155, v155
	v_cvt_pk_bf16_f32 v160, v147, v166
	v_cvt_pk_bf16_f32 v161, v168, v176
	v_cvt_pk_bf16_f32 v162, v155, v167
	v_cvt_pk_bf16_f32 v163, v175, v34
	v_mul_f32_e32 v34, 0xbfb8aa3b, v143
	v_addc_co_u32_e32 v165, vcc, 0, v165, vcc
	global_store_dwordx4 v[164:165], v[160:163], off
	v_mul_f32_e32 v164, v34, v20
	v_exp_f32_e32 v164, v164
	v_mul_f32_e32 v160, v34, v19
	v_mul_f32_e32 v162, v34, v11
	v_exp_f32_e32 v160, v160
	v_exp_f32_e32 v162, v162
	v_mul_f32_e32 v161, v34, v7
	v_mul_f32_e32 v163, v34, v3
	v_add_f32_e32 v160, 1.0, v160
	v_exp_f32_e32 v161, v161
	v_exp_f32_e32 v163, v163
	v_add_f32_e32 v162, 1.0, v162
	v_rcp_f32_e32 v160, v160
	v_rcp_f32_e32 v162, v162
	v_add_f32_e32 v161, 1.0, v161
	v_add_f32_e32 v163, 1.0, v163
	v_mul_f32_e32 v160, v161, v160
	v_rcp_f32_e32 v166, v161
	v_mul_f32_e32 v162, v163, v162
	v_rcp_f32_e32 v167, v163
	v_add_f32_e32 v161, 1.0, v164
	v_mul_f32_e32 v163, v34, v8
	v_mul_f32_e32 v164, v34, v12
	v_exp_f32_e32 v163, v163
	v_exp_f32_e32 v164, v164
	v_rcp_f32_e32 v161, v161
	v_mul_f32_e32 v165, v34, v4
	v_exp_f32_e32 v165, v165
	v_add_f32_e32 v163, 1.0, v163
	v_add_f32_e32 v164, 1.0, v164
	v_mul_f32_e32 v169, v34, v9
	v_mul_f32_e32 v161, v163, v161
	v_rcp_f32_e32 v168, v163
	v_rcp_f32_e32 v163, v164
	v_exp_f32_e32 v169, v169
	v_add_f32_e32 v165, 1.0, v165
	v_mul_f32_e32 v164, v34, v21
	v_mul_f32_e32 v163, v165, v163
	v_rcp_f32_e32 v175, v165
	v_add_f32_e32 v165, 1.0, v169
	v_mul_f32_e32 v169, v34, v13
	v_mul_f32_e32 v145, v34, v18
	v_mul_f32_e32 v149, v34, v10
	v_exp_f32_e32 v164, v164
	v_exp_f32_e32 v169, v169
	v_exp_f32_e32 v145, v145
	v_exp_f32_e32 v149, v149
	v_mul_f32_e32 v147, v34, v6
	v_mul_f32_e32 v155, v34, v2
	v_mul_f32_e32 v34, v34, v5
	v_add_f32_e32 v164, 1.0, v164
	v_exp_f32_e32 v34, v34
	v_add_f32_e32 v169, 1.0, v169
	v_add_f32_e32 v145, 1.0, v145
	v_exp_f32_e32 v147, v147
	v_exp_f32_e32 v155, v155
	v_add_f32_e32 v149, 1.0, v149
	v_rcp_f32_e32 v164, v164
	v_rcp_f32_e32 v169, v169
	v_rcp_f32_e32 v145, v145
	v_rcp_f32_e32 v149, v149
	s_addk_i32 s8, 0xfe4e
	v_add_f32_e32 v34, 1.0, v34
	s_ashr_i32 s9, s8, 31
	v_add_f32_e32 v147, 1.0, v147
	v_add_f32_e32 v155, 1.0, v155
	v_mul_f32_e32 v164, v165, v164
	v_rcp_f32_e32 v176, v165
	v_mul_f32_e32 v165, v34, v169
	s_lshl_b64 s[8:9], s[8:9], 13
	v_mul_f32_e32 v145, v147, v145
	v_mul_f32_e32 v149, v155, v149
	v_cvt_pk_bf16_f32 v160, v145, v160
	v_cvt_pk_bf16_f32 v161, v161, v164
	v_cvt_pk_bf16_f32 v162, v149, v162
	v_cvt_pk_bf16_f32 v163, v163, v165
	v_lshl_add_u64 v[164:165], v[150:151], 0, s[8:9]
	global_store_dwordx4 v[164:165], v[160:163], off
	v_add_co_u32_e32 v164, vcc, 0x2000, v164
	v_rcp_f32_e32 v147, v147
	s_nop 0
	v_addc_co_u32_e32 v165, vcc, 0, v165, vcc
	v_rcp_f32_e32 v155, v155
	v_rcp_f32_e32 v34, v34
	v_cvt_pk_bf16_f32 v160, v147, v166
	v_cvt_pk_bf16_f32 v161, v168, v176
	v_cvt_pk_bf16_f32 v162, v155, v167
	v_cvt_pk_bf16_f32 v163, v175, v34
	global_store_dwordx4 v[164:165], v[160:163], off

.LBB0_348:
	v_lshl_or_b32 v162, s34, 7, v171
	v_ashrrev_i32_e32 v163, 31, v162
	v_mov_b64_e32 v[160:161], s[12:13]
	v_mad_i64_i32 v[164:165], s[8:9], v174, s68, v[160:161]
	v_lshlrev_b64 v[162:163], 1, v[162:163]
	s_waitcnt vmcnt(8)
	v_mul_f32_e32 v34, v158, v158
	v_pk_mul_f32 v[126:127], v[126:127], v[134:135]
	v_pk_mul_f32 v[124:125], v[124:125], v[132:133]
	v_pk_mul_f32 v[122:123], v[122:123], v[130:131]
	v_pk_mul_f32 v[120:121], v[120:121], v[128:129]
	v_lshl_add_u64 v[164:165], v[164:165], 0, v[162:163]
	v_pk_mul_f32 v[126:127], v[34:35], v[126:127] op_sel_hi:[0,1]
	v_pk_mul_f32 v[124:125], v[34:35], v[124:125] op_sel_hi:[0,1]
	v_pk_mul_f32 v[128:129], v[34:35], v[122:123] op_sel_hi:[0,1]
	v_pk_mul_f32 v[122:123], v[34:35], v[120:121] op_sel_hi:[0,1]
	v_cvt_pk_bf16_f32 v120, v124, v125
	v_cvt_pk_bf16_f32 v121, v126, v127
	v_or_b32_e32 v34, 16, v174
	v_cvt_pk_bf16_f32 v122, v122, v123
	v_cvt_pk_bf16_f32 v123, v128, v129
	global_store_dwordx4 v[164:165], v[120:123], off
	v_pk_mul_f32 v[110:111], v[110:111], v[118:119]
	v_pk_mul_f32 v[108:109], v[108:109], v[116:117]
	v_mad_i64_i32 v[120:121], s[8:9], v34, s68, v[160:161]
	v_mul_f32_e32 v34, v159, v159
	v_pk_mul_f32 v[106:107], v[106:107], v[114:115]
	v_pk_mul_f32 v[104:105], v[104:105], v[112:113]
	v_lshl_add_u64 v[120:121], v[120:121], 0, v[162:163]
	v_pk_mul_f32 v[110:111], v[34:35], v[110:111] op_sel_hi:[0,1]
	v_pk_mul_f32 v[108:109], v[34:35], v[108:109] op_sel_hi:[0,1]
	v_pk_mul_f32 v[112:113], v[34:35], v[106:107] op_sel_hi:[0,1]
	v_pk_mul_f32 v[106:107], v[34:35], v[104:105] op_sel_hi:[0,1]
	v_cvt_pk_bf16_f32 v104, v108, v109
	v_cvt_pk_bf16_f32 v105, v110, v111
	v_or_b32_e32 v34, 32, v174
	v_cvt_pk_bf16_f32 v106, v106, v107
	v_cvt_pk_bf16_f32 v107, v112, v113
	global_store_dwordx4 v[120:121], v[104:107], off
	v_pk_mul_f32 v[94:95], v[94:95], v[102:103]
	v_pk_mul_f32 v[92:93], v[92:93], v[100:101]
	v_mad_i64_i32 v[104:105], s[8:9], v34, s68, v[160:161]
	v_mul_f32_e32 v34, v154, v154
	v_pk_mul_f32 v[90:91], v[90:91], v[98:99]
	v_pk_mul_f32 v[88:89], v[88:89], v[96:97]
	v_lshl_add_u64 v[104:105], v[104:105], 0, v[162:163]
	v_pk_mul_f32 v[94:95], v[34:35], v[94:95] op_sel_hi:[0,1]
	v_pk_mul_f32 v[92:93], v[34:35], v[92:93] op_sel_hi:[0,1]
	v_pk_mul_f32 v[96:97], v[34:35], v[90:91] op_sel_hi:[0,1]
	v_pk_mul_f32 v[90:91], v[34:35], v[88:89] op_sel_hi:[0,1]
	v_cvt_pk_bf16_f32 v88, v92, v93
	v_cvt_pk_bf16_f32 v89, v94, v95
	v_or_b32_e32 v34, 48, v174
	v_cvt_pk_bf16_f32 v90, v90, v91
	v_cvt_pk_bf16_f32 v91, v96, v97
	global_store_dwordx4 v[104:105], v[88:91], off
	v_pk_mul_f32 v[78:79], v[78:79], v[86:87]
	v_pk_mul_f32 v[76:77], v[76:77], v[84:85]
	v_mad_i64_i32 v[88:89], s[8:9], v34, s68, v[160:161]
	v_mul_f32_e32 v34, v148, v148
	v_pk_mul_f32 v[74:75], v[74:75], v[82:83]
	v_pk_mul_f32 v[72:73], v[72:73], v[80:81]
	v_lshl_add_u64 v[88:89], v[88:89], 0, v[162:163]
	v_pk_mul_f32 v[78:79], v[34:35], v[78:79] op_sel_hi:[0,1]
	v_pk_mul_f32 v[76:77], v[34:35], v[76:77] op_sel_hi:[0,1]
	v_pk_mul_f32 v[80:81], v[34:35], v[74:75] op_sel_hi:[0,1]
	v_pk_mul_f32 v[74:75], v[34:35], v[72:73] op_sel_hi:[0,1]
	v_cvt_pk_bf16_f32 v72, v76, v77
	v_cvt_pk_bf16_f32 v73, v78, v79
	v_add_u32_e32 v34, 0x80, v174
	v_cvt_pk_bf16_f32 v74, v74, v75
	v_cvt_pk_bf16_f32 v75, v80, v81
	global_store_dwordx4 v[88:89], v[72:75], off
	v_pk_mul_f32 v[62:63], v[62:63], v[70:71]
	v_pk_mul_f32 v[60:61], v[60:61], v[68:69]
	v_mad_i64_i32 v[72:73], s[8:9], v34, s68, v[160:161]
	v_mul_f32_e32 v34, v146, v146
	v_pk_mul_f32 v[58:59], v[58:59], v[66:67]
	v_pk_mul_f32 v[56:57], v[56:57], v[64:65]
	v_lshl_add_u64 v[72:73], v[72:73], 0, v[162:163]
	v_pk_mul_f32 v[62:63], v[34:35], v[62:63] op_sel_hi:[0,1]
	v_pk_mul_f32 v[60:61], v[34:35], v[60:61] op_sel_hi:[0,1]
	v_pk_mul_f32 v[64:65], v[34:35], v[58:59] op_sel_hi:[0,1]
	v_pk_mul_f32 v[58:59], v[34:35], v[56:57] op_sel_hi:[0,1]
	v_cvt_pk_bf16_f32 v56, v60, v61
	v_cvt_pk_bf16_f32 v57, v62, v63
	v_add_u32_e32 v34, 0x90, v174
	v_cvt_pk_bf16_f32 v58, v58, v59
	v_cvt_pk_bf16_f32 v59, v64, v65
	global_store_dwordx4 v[72:73], v[56:59], off
	v_pk_mul_f32 v[46:47], v[46:47], v[54:55]
	v_pk_mul_f32 v[44:45], v[44:45], v[52:53]
	v_mad_i64_i32 v[56:57], s[8:9], v34, s68, v[160:161]
	v_mul_f32_e32 v34, v144, v144
	v_pk_mul_f32 v[42:43], v[42:43], v[50:51]
	v_pk_mul_f32 v[40:41], v[40:41], v[48:49]
	v_lshl_add_u64 v[56:57], v[56:57], 0, v[162:163]
	v_pk_mul_f32 v[46:47], v[34:35], v[46:47] op_sel_hi:[0,1]
	v_pk_mul_f32 v[44:45], v[34:35], v[44:45] op_sel_hi:[0,1]
	v_pk_mul_f32 v[48:49], v[34:35], v[42:43] op_sel_hi:[0,1]
	v_pk_mul_f32 v[42:43], v[34:35], v[40:41] op_sel_hi:[0,1]
	v_cvt_pk_bf16_f32 v40, v44, v45
	v_cvt_pk_bf16_f32 v41, v46, v47
	v_add_u32_e32 v34, 0xa0, v174
	v_cvt_pk_bf16_f32 v42, v42, v43
	v_cvt_pk_bf16_f32 v43, v48, v49
	global_store_dwordx4 v[56:57], v[40:43], off
	v_pk_mul_f32 v[26:27], v[26:27], v[36:37]
	v_pk_mul_f32 v[24:25], v[24:25], v[32:33]
	v_mad_i64_i32 v[40:41], s[8:9], v34, s68, v[160:161]
	v_mul_f32_e32 v34, v142, v142
	v_pk_mul_f32 v[22:23], v[22:23], v[30:31]
	v_lshl_add_u64 v[40:41], v[40:41], 0, v[162:163]
	v_pk_mul_f32 v[28:29], v[28:29], v[38:39]
	v_pk_mul_f32 v[26:27], v[34:35], v[26:27] op_sel_hi:[0,1]
	v_pk_mul_f32 v[30:31], v[34:35], v[24:25] op_sel_hi:[0,1]
	v_pk_mul_f32 v[24:25], v[34:35], v[22:23] op_sel_hi:[0,1]
	v_cvt_pk_bf16_f32 v22, v26, v27
	v_pk_mul_f32 v[28:29], v[34:35], v[28:29] op_sel_hi:[0,1]
	v_cvt_pk_bf16_f32 v23, v28, v29
	v_cvt_pk_bf16_f32 v24, v24, v25
	v_cvt_pk_bf16_f32 v25, v30, v31
	global_store_dwordx4 v[40:41], v[22:25], off
	v_pk_mul_f32 v[4:5], v[4:5], v[12:13]
	v_pk_mul_f32 v[2:3], v[2:3], v[10:11]
	v_add_u32_e32 v22, 0xb0, v174
	v_mad_i64_i32 v[22:23], s[8:9], v22, s68, v[160:161]
	v_mul_f32_e32 v24, v143, v143
	v_lshl_add_u64 v[22:23], v[22:23], 0, v[162:163]
	v_pk_mul_f32 v[8:9], v[8:9], v[20:21]
	v_pk_mul_f32 v[6:7], v[6:7], v[18:19]
	v_pk_mul_f32 v[10:11], v[24:25], v[4:5] op_sel_hi:[0,1]
	v_pk_mul_f32 v[4:5], v[24:25], v[2:3] op_sel_hi:[0,1]
	v_pk_mul_f32 v[8:9], v[24:25], v[8:9] op_sel_hi:[0,1]
	v_pk_mul_f32 v[6:7], v[24:25], v[6:7] op_sel_hi:[0,1]
	v_cvt_pk_bf16_f32 v2, v6, v7
	v_cvt_pk_bf16_f32 v3, v8, v9
	v_cvt_pk_bf16_f32 v4, v4, v5
	v_cvt_pk_bf16_f32 v5, v10, v11
	global_store_dwordx4 v[22:23], v[2:5], off

.LBB0_1667:
	v_mov_b32_e32 v166, v124
	v_mov_b32_e32 v167, v132
	s_waitcnt vmcnt(8)
	v_pk_mul_f32 v[166:167], v[160:161], v[166:167] op_sel_hi:[0,1]
	v_mul_f32_e32 v124, 0xbfb8aa3b, v167
	v_exp_f32_e32 v124, v124
	v_mov_b32_e32 v132, v125
	v_lshl_or_b32 v162, s51, 7, v147
	v_lshl_add_u32 v151, s52, 8, v17
	v_add_f32_e32 v124, 1.0, v124
	v_rcp_f32_e32 v124, v124
	v_ashrrev_i32_e32 v163, 31, v162
	v_mov_b64_e32 v[158:159], s[8:9]
	v_mad_i64_i32 v[164:165], s[42:43], v151, s19, v[158:159]
	v_mul_f32_e32 v124, v167, v124
	v_mul_f32_e32 v153, v166, v124
	v_mov_b32_e32 v166, v120
	v_mov_b32_e32 v167, v128
	v_pk_mul_f32 v[166:167], v[160:161], v[166:167] op_sel_hi:[0,1]
	v_mul_f32_e32 v120, 0xbfb8aa3b, v167
	v_exp_f32_e32 v120, v120
	v_pk_mul_f32 v[124:125], v[160:161], v[132:133] op_sel_hi:[0,1]
	v_mov_b32_e32 v128, v121
	s_andn2_b64 vcc, exec, s[38:39]
	v_add_f32_e32 v120, 1.0, v120
	v_rcp_f32_e32 v120, v120
	v_readlane_b32 s60, v252, 49
	v_mul_f32_e32 v120, v167, v120
	v_mul_f32_e32 v155, v166, v120
	v_mul_f32_e32 v120, 0xbfb8aa3b, v125
	v_exp_f32_e32 v120, v120
	s_nop 0
	v_add_f32_e32 v120, 1.0, v120
	v_rcp_f32_e32 v120, v120
	s_nop 0
	v_mul_f32_e32 v120, v125, v120
	v_mul_f32_e32 v124, v124, v120
	v_pk_mul_f32 v[120:121], v[160:161], v[128:129] op_sel_hi:[0,1]
	v_mul_f32_e32 v125, 0xbfb8aa3b, v121
	v_exp_f32_e32 v125, v125
	s_nop 0
	v_add_f32_e32 v125, 1.0, v125
	v_rcp_f32_e32 v125, v125
	s_nop 0
	v_mul_f32_e32 v121, v121, v125
	v_mul_f32_e32 v125, v120, v121
	v_mov_b32_e32 v120, v126
	v_mov_b32_e32 v121, v134
	v_pk_mul_f32 v[120:121], v[160:161], v[120:121] op_sel_hi:[0,1]
	v_mul_f32_e32 v126, 0xbfb8aa3b, v121
	v_exp_f32_e32 v126, v126
	v_mov_b32_e32 v134, v127
	v_add_f32_e32 v126, 1.0, v126
	v_rcp_f32_e32 v126, v126
	s_nop 0
	v_mul_f32_e32 v121, v121, v126
	v_mul_f32_e32 v128, v120, v121
	v_mov_b32_e32 v120, v122
	v_mov_b32_e32 v121, v130
	v_pk_mul_f32 v[120:121], v[160:161], v[120:121] op_sel_hi:[0,1]
	v_mul_f32_e32 v122, 0xbfb8aa3b, v121
	v_exp_f32_e32 v122, v122
	v_mov_b32_e32 v130, v123
	v_add_f32_e32 v122, 1.0, v122
	v_rcp_f32_e32 v122, v122
	s_nop 0
	v_mul_f32_e32 v121, v121, v122
	v_mul_f32_e32 v129, v120, v121
	v_pk_mul_f32 v[120:121], v[160:161], v[134:135] op_sel_hi:[0,1]
	v_mul_f32_e32 v122, 0xbfb8aa3b, v121
	v_exp_f32_e32 v122, v122
	s_nop 0
	v_add_f32_e32 v122, 1.0, v122
	v_rcp_f32_e32 v122, v122
	s_nop 0
	v_mul_f32_e32 v121, v121, v122
	v_mul_f32_e32 v132, v120, v121
	v_pk_mul_f32 v[120:121], v[160:161], v[130:131] op_sel_hi:[0,1]
	v_mul_f32_e32 v122, 0xbfb8aa3b, v121
	v_exp_f32_e32 v122, v122
	s_nop 0
	v_add_f32_e32 v122, 1.0, v122
	v_rcp_f32_e32 v122, v122
	s_nop 0
	v_mul_f32_e32 v121, v121, v122
	v_mul_f32_e32 v130, v120, v121
	v_lshlrev_b64 v[120:121], 1, v[162:163]
	v_lshl_add_u64 v[126:127], v[164:165], 0, v[120:121]
	v_cvt_pk_bf16_f32 v122, v153, v124
	v_cvt_pk_bf16_f32 v123, v128, v132
	v_cvt_pk_bf16_f32 v124, v155, v125
	v_cvt_pk_bf16_f32 v125, v129, v130
	global_store_dwordx4 v[126:127], v[122:125], off
	s_nop 1
	v_mov_b32_e32 v124, v108
	v_mov_b32_e32 v125, v116
	v_pk_mul_f32 v[124:125], v[156:157], v[124:125] op_sel_hi:[0,1]
	v_mul_f32_e32 v108, 0xbfb8aa3b, v125
	v_exp_f32_e32 v108, v108
	v_mov_b32_e32 v116, v109
	v_or_b32_e32 v122, 16, v151
	v_mad_i64_i32 v[122:123], s[42:43], v122, s19, v[158:159]
	v_add_f32_e32 v108, 1.0, v108
	v_rcp_f32_e32 v108, v108
	s_nop 0
	v_mul_f32_e32 v108, v125, v108
	v_mul_f32_e32 v126, v124, v108
	v_mov_b32_e32 v124, v104
	v_mov_b32_e32 v125, v112
	v_pk_mul_f32 v[124:125], v[156:157], v[124:125] op_sel_hi:[0,1]
	v_mul_f32_e32 v104, 0xbfb8aa3b, v125
	v_exp_f32_e32 v104, v104
	v_pk_mul_f32 v[108:109], v[156:157], v[116:117] op_sel_hi:[0,1]
	v_mov_b32_e32 v112, v105
	v_add_f32_e32 v104, 1.0, v104
	v_rcp_f32_e32 v104, v104
	s_nop 0
	v_mul_f32_e32 v104, v125, v104
	v_mul_f32_e32 v124, v124, v104
	v_mul_f32_e32 v104, 0xbfb8aa3b, v109
	v_exp_f32_e32 v104, v104
	s_nop 0
	v_add_f32_e32 v104, 1.0, v104
	v_rcp_f32_e32 v104, v104
	s_nop 0
	v_mul_f32_e32 v104, v109, v104
	v_mul_f32_e32 v116, v108, v104
	v_pk_mul_f32 v[104:105], v[156:157], v[112:113] op_sel_hi:[0,1]
	v_mul_f32_e32 v108, 0xbfb8aa3b, v105
	v_exp_f32_e32 v108, v108
	s_nop 0
	v_add_f32_e32 v108, 1.0, v108
	v_rcp_f32_e32 v108, v108
	s_nop 0
	v_mul_f32_e32 v105, v105, v108
	v_mul_f32_e32 v112, v104, v105
	v_mov_b32_e32 v104, v110
	v_mov_b32_e32 v105, v118
	v_pk_mul_f32 v[104:105], v[156:157], v[104:105] op_sel_hi:[0,1]
	v_mul_f32_e32 v108, 0xbfb8aa3b, v105
	v_exp_f32_e32 v108, v108
	v_mov_b32_e32 v118, v111
	v_add_f32_e32 v108, 1.0, v108
	v_rcp_f32_e32 v108, v108
	s_nop 0
	v_mul_f32_e32 v105, v105, v108
	v_mul_f32_e32 v110, v104, v105
	v_mov_b32_e32 v104, v106
	v_mov_b32_e32 v105, v114
	v_pk_mul_f32 v[104:105], v[156:157], v[104:105] op_sel_hi:[0,1]
	v_mul_f32_e32 v106, 0xbfb8aa3b, v105
	v_exp_f32_e32 v106, v106
	v_mov_b32_e32 v114, v107
	v_lshl_add_u64 v[108:109], v[122:123], 0, v[120:121]
	v_add_f32_e32 v106, 1.0, v106
	v_rcp_f32_e32 v106, v106
	s_nop 0
	v_mul_f32_e32 v105, v105, v106
	v_mul_f32_e32 v113, v104, v105
	v_pk_mul_f32 v[104:105], v[156:157], v[118:119] op_sel_hi:[0,1]
	v_mul_f32_e32 v106, 0xbfb8aa3b, v105
	v_exp_f32_e32 v106, v106
	s_nop 0
	v_add_f32_e32 v106, 1.0, v106
	v_rcp_f32_e32 v106, v106
	s_nop 0
	v_mul_f32_e32 v105, v105, v106
	v_mul_f32_e32 v106, v104, v105
	v_pk_mul_f32 v[104:105], v[156:157], v[114:115] op_sel_hi:[0,1]
	v_mul_f32_e32 v107, 0xbfb8aa3b, v105
	v_exp_f32_e32 v107, v107
	s_nop 0
	v_add_f32_e32 v107, 1.0, v107
	v_rcp_f32_e32 v107, v107
	s_nop 0
	v_mul_f32_e32 v105, v105, v107
	v_mul_f32_e32 v107, v104, v105
	v_cvt_pk_bf16_f32 v104, v126, v116
	v_cvt_pk_bf16_f32 v105, v110, v106
	v_cvt_pk_bf16_f32 v106, v124, v112
	v_cvt_pk_bf16_f32 v107, v113, v107
	global_store_dwordx4 v[108:109], v[104:107], off
	s_nop 1
	v_mov_b32_e32 v106, v92
	v_mov_b32_e32 v107, v100
	v_pk_mul_f32 v[106:107], v[154:155], v[106:107] op_sel_hi:[0,1]
	v_mul_f32_e32 v92, 0xbfb8aa3b, v107
	v_exp_f32_e32 v92, v92
	v_mov_b32_e32 v100, v93
	v_or_b32_e32 v104, 32, v151
	v_mad_i64_i32 v[104:105], s[42:43], v104, s19, v[158:159]
	v_add_f32_e32 v92, 1.0, v92
	v_rcp_f32_e32 v92, v92
	s_nop 0
	v_mul_f32_e32 v92, v107, v92
	v_mul_f32_e32 v108, v106, v92
	v_mov_b32_e32 v106, v88
	v_mov_b32_e32 v107, v96
	v_pk_mul_f32 v[106:107], v[154:155], v[106:107] op_sel_hi:[0,1]
	v_mul_f32_e32 v88, 0xbfb8aa3b, v107
	v_exp_f32_e32 v88, v88
	v_pk_mul_f32 v[92:93], v[154:155], v[100:101] op_sel_hi:[0,1]
	v_mov_b32_e32 v96, v89
	v_add_f32_e32 v88, 1.0, v88
	v_rcp_f32_e32 v88, v88
	s_nop 0
	v_mul_f32_e32 v88, v107, v88
	v_mul_f32_e32 v106, v106, v88
	v_mul_f32_e32 v88, 0xbfb8aa3b, v93
	v_exp_f32_e32 v88, v88
	s_nop 0
	v_add_f32_e32 v88, 1.0, v88
	v_rcp_f32_e32 v88, v88
	s_nop 0
	v_mul_f32_e32 v88, v93, v88
	v_mul_f32_e32 v100, v92, v88
	v_pk_mul_f32 v[88:89], v[154:155], v[96:97] op_sel_hi:[0,1]
	v_mul_f32_e32 v92, 0xbfb8aa3b, v89
	v_exp_f32_e32 v92, v92
	s_nop 0
	v_add_f32_e32 v92, 1.0, v92
	v_rcp_f32_e32 v92, v92
	s_nop 0
	v_mul_f32_e32 v89, v89, v92
	v_mul_f32_e32 v96, v88, v89
	v_mov_b32_e32 v88, v94
	v_mov_b32_e32 v89, v102
	v_pk_mul_f32 v[88:89], v[154:155], v[88:89] op_sel_hi:[0,1]
	v_mul_f32_e32 v92, 0xbfb8aa3b, v89
	v_exp_f32_e32 v92, v92
	v_mov_b32_e32 v102, v95
	v_add_f32_e32 v92, 1.0, v92
	v_rcp_f32_e32 v92, v92
	s_nop 0
	v_mul_f32_e32 v89, v89, v92
	v_mul_f32_e32 v94, v88, v89
	v_mov_b32_e32 v88, v90
	v_mov_b32_e32 v89, v98
	v_pk_mul_f32 v[88:89], v[154:155], v[88:89] op_sel_hi:[0,1]
	v_mul_f32_e32 v90, 0xbfb8aa3b, v89
	v_exp_f32_e32 v90, v90
	v_mov_b32_e32 v98, v91
	v_lshl_add_u64 v[92:93], v[104:105], 0, v[120:121]
	v_add_f32_e32 v90, 1.0, v90
	v_rcp_f32_e32 v90, v90
	s_nop 0
	v_mul_f32_e32 v89, v89, v90
	v_mul_f32_e32 v97, v88, v89
	v_pk_mul_f32 v[88:89], v[154:155], v[102:103] op_sel_hi:[0,1]
	v_mul_f32_e32 v90, 0xbfb8aa3b, v89
	v_exp_f32_e32 v90, v90
	s_nop 0
	v_add_f32_e32 v90, 1.0, v90
	v_rcp_f32_e32 v90, v90
	s_nop 0
	v_mul_f32_e32 v89, v89, v90
	v_mul_f32_e32 v90, v88, v89
	v_pk_mul_f32 v[88:89], v[154:155], v[98:99] op_sel_hi:[0,1]
	v_mul_f32_e32 v91, 0xbfb8aa3b, v89
	v_exp_f32_e32 v91, v91
	s_nop 0
	v_add_f32_e32 v91, 1.0, v91
	v_rcp_f32_e32 v91, v91
	s_nop 0
	v_mul_f32_e32 v89, v89, v91
	v_mul_f32_e32 v91, v88, v89
	v_cvt_pk_bf16_f32 v88, v108, v100
	v_cvt_pk_bf16_f32 v89, v94, v90
	v_cvt_pk_bf16_f32 v90, v106, v96
	v_cvt_pk_bf16_f32 v91, v97, v91
	global_store_dwordx4 v[92:93], v[88:91], off
	s_nop 1
	v_mov_b32_e32 v90, v76
	v_mov_b32_e32 v91, v84
	v_pk_mul_f32 v[90:91], v[152:153], v[90:91] op_sel_hi:[0,1]
	v_mul_f32_e32 v76, 0xbfb8aa3b, v91
	v_exp_f32_e32 v76, v76
	v_mov_b32_e32 v84, v77
	v_or_b32_e32 v88, 48, v151
	v_mad_i64_i32 v[88:89], s[42:43], v88, s19, v[158:159]
	v_add_f32_e32 v76, 1.0, v76
	v_rcp_f32_e32 v76, v76
	s_nop 0
	v_mul_f32_e32 v76, v91, v76
	v_mul_f32_e32 v92, v90, v76
	v_mov_b32_e32 v90, v72
	v_mov_b32_e32 v91, v80
	v_pk_mul_f32 v[90:91], v[152:153], v[90:91] op_sel_hi:[0,1]
	v_mul_f32_e32 v72, 0xbfb8aa3b, v91
	v_exp_f32_e32 v72, v72
	v_pk_mul_f32 v[76:77], v[152:153], v[84:85] op_sel_hi:[0,1]
	v_mov_b32_e32 v80, v73
	v_add_f32_e32 v72, 1.0, v72
	v_rcp_f32_e32 v72, v72
	s_nop 0
	v_mul_f32_e32 v72, v91, v72
	v_mul_f32_e32 v90, v90, v72
	v_mul_f32_e32 v72, 0xbfb8aa3b, v77
	v_exp_f32_e32 v72, v72
	s_nop 0
	v_add_f32_e32 v72, 1.0, v72
	v_rcp_f32_e32 v72, v72
	s_nop 0
	v_mul_f32_e32 v72, v77, v72
	v_mul_f32_e32 v84, v76, v72
	v_pk_mul_f32 v[72:73], v[152:153], v[80:81] op_sel_hi:[0,1]
	v_mul_f32_e32 v76, 0xbfb8aa3b, v73
	v_exp_f32_e32 v76, v76
	s_nop 0
	v_add_f32_e32 v76, 1.0, v76
	v_rcp_f32_e32 v76, v76
	s_nop 0
	v_mul_f32_e32 v73, v73, v76
	v_mul_f32_e32 v80, v72, v73
	v_mov_b32_e32 v72, v78
	v_mov_b32_e32 v73, v86
	v_pk_mul_f32 v[72:73], v[152:153], v[72:73] op_sel_hi:[0,1]
	v_mul_f32_e32 v76, 0xbfb8aa3b, v73
	v_exp_f32_e32 v76, v76
	v_mov_b32_e32 v86, v79
	v_add_f32_e32 v76, 1.0, v76
	v_rcp_f32_e32 v76, v76
	s_nop 0
	v_mul_f32_e32 v73, v73, v76
	v_mul_f32_e32 v78, v72, v73
	v_mov_b32_e32 v72, v74
	v_mov_b32_e32 v73, v82
	v_pk_mul_f32 v[72:73], v[152:153], v[72:73] op_sel_hi:[0,1]
	v_mul_f32_e32 v74, 0xbfb8aa3b, v73
	v_exp_f32_e32 v74, v74
	v_mov_b32_e32 v82, v75
	v_lshl_add_u64 v[76:77], v[88:89], 0, v[120:121]
	v_add_f32_e32 v74, 1.0, v74
	v_rcp_f32_e32 v74, v74
	s_nop 0
	v_mul_f32_e32 v73, v73, v74
	v_mul_f32_e32 v81, v72, v73
	v_pk_mul_f32 v[72:73], v[152:153], v[86:87] op_sel_hi:[0,1]
	v_mul_f32_e32 v74, 0xbfb8aa3b, v73
	v_exp_f32_e32 v74, v74
	s_nop 0
	v_add_f32_e32 v74, 1.0, v74
	v_rcp_f32_e32 v74, v74
	s_nop 0
	v_mul_f32_e32 v73, v73, v74
	v_mul_f32_e32 v74, v72, v73
	v_pk_mul_f32 v[72:73], v[152:153], v[82:83] op_sel_hi:[0,1]
	v_mul_f32_e32 v75, 0xbfb8aa3b, v73
	v_exp_f32_e32 v75, v75
	s_nop 0
	v_add_f32_e32 v75, 1.0, v75
	v_rcp_f32_e32 v75, v75
	s_nop 0
	v_mul_f32_e32 v73, v73, v75
	v_mul_f32_e32 v75, v72, v73
	v_cvt_pk_bf16_f32 v72, v92, v84
	v_cvt_pk_bf16_f32 v73, v78, v74
	v_cvt_pk_bf16_f32 v74, v90, v80
	v_cvt_pk_bf16_f32 v75, v81, v75
	global_store_dwordx4 v[76:77], v[72:75], off
	s_nop 1
	v_mov_b32_e32 v74, v60
	v_mov_b32_e32 v75, v68
	v_pk_mul_f32 v[74:75], v[150:151], v[74:75] op_sel_hi:[0,1]
	v_mul_f32_e32 v60, 0xbfb8aa3b, v75
	v_exp_f32_e32 v60, v60
	v_mov_b32_e32 v68, v61
	v_add_u32_e32 v72, 0x80, v151
	v_mad_i64_i32 v[72:73], s[42:43], v72, s19, v[158:159]
	v_add_f32_e32 v60, 1.0, v60
	v_rcp_f32_e32 v60, v60
	s_nop 0
	v_mul_f32_e32 v60, v75, v60
	v_mul_f32_e32 v76, v74, v60
	v_mov_b32_e32 v74, v56
	v_mov_b32_e32 v75, v64
	v_pk_mul_f32 v[74:75], v[150:151], v[74:75] op_sel_hi:[0,1]
	v_mul_f32_e32 v56, 0xbfb8aa3b, v75
	v_exp_f32_e32 v56, v56
	v_pk_mul_f32 v[60:61], v[150:151], v[68:69] op_sel_hi:[0,1]
	v_mov_b32_e32 v64, v57
	v_add_f32_e32 v56, 1.0, v56
	v_rcp_f32_e32 v56, v56
	s_nop 0
	v_mul_f32_e32 v56, v75, v56
	v_mul_f32_e32 v74, v74, v56
	v_mul_f32_e32 v56, 0xbfb8aa3b, v61
	v_exp_f32_e32 v56, v56
	s_nop 0
	v_add_f32_e32 v56, 1.0, v56
	v_rcp_f32_e32 v56, v56
	s_nop 0
	v_mul_f32_e32 v56, v61, v56
	v_mul_f32_e32 v68, v60, v56
	v_pk_mul_f32 v[56:57], v[150:151], v[64:65] op_sel_hi:[0,1]
	v_mul_f32_e32 v60, 0xbfb8aa3b, v57
	v_exp_f32_e32 v60, v60
	s_nop 0
	v_add_f32_e32 v60, 1.0, v60
	v_rcp_f32_e32 v60, v60
	s_nop 0
	v_mul_f32_e32 v57, v57, v60
	v_mul_f32_e32 v64, v56, v57
	v_mov_b32_e32 v56, v62
	v_mov_b32_e32 v57, v70
	v_pk_mul_f32 v[56:57], v[150:151], v[56:57] op_sel_hi:[0,1]
	v_mul_f32_e32 v60, 0xbfb8aa3b, v57
	v_exp_f32_e32 v60, v60
	v_mov_b32_e32 v70, v63
	v_add_f32_e32 v60, 1.0, v60
	v_rcp_f32_e32 v60, v60
	s_nop 0
	v_mul_f32_e32 v57, v57, v60
	v_mul_f32_e32 v62, v56, v57
	v_mov_b32_e32 v56, v58
	v_mov_b32_e32 v57, v66
	v_pk_mul_f32 v[56:57], v[150:151], v[56:57] op_sel_hi:[0,1]
	v_mul_f32_e32 v58, 0xbfb8aa3b, v57
	v_exp_f32_e32 v58, v58
	v_mov_b32_e32 v66, v59
	v_lshl_add_u64 v[60:61], v[72:73], 0, v[120:121]
	v_add_f32_e32 v58, 1.0, v58
	v_rcp_f32_e32 v58, v58
	s_nop 0
	v_mul_f32_e32 v57, v57, v58
	v_mul_f32_e32 v65, v56, v57
	v_pk_mul_f32 v[56:57], v[150:151], v[70:71] op_sel_hi:[0,1]
	v_mul_f32_e32 v58, 0xbfb8aa3b, v57
	v_exp_f32_e32 v58, v58
	s_nop 0
	v_add_f32_e32 v58, 1.0, v58
	v_rcp_f32_e32 v58, v58
	s_nop 0
	v_mul_f32_e32 v57, v57, v58
	v_mul_f32_e32 v58, v56, v57
	v_pk_mul_f32 v[56:57], v[150:151], v[66:67] op_sel_hi:[0,1]
	v_mul_f32_e32 v59, 0xbfb8aa3b, v57
	v_exp_f32_e32 v59, v59
	s_nop 0
	v_add_f32_e32 v59, 1.0, v59
	v_rcp_f32_e32 v59, v59
	s_nop 0
	v_mul_f32_e32 v57, v57, v59
	v_mul_f32_e32 v59, v56, v57
	v_cvt_pk_bf16_f32 v56, v76, v68
	v_cvt_pk_bf16_f32 v57, v62, v58
	v_cvt_pk_bf16_f32 v58, v74, v64
	v_cvt_pk_bf16_f32 v59, v65, v59
	global_store_dwordx4 v[60:61], v[56:59], off
	s_nop 1
	v_mov_b32_e32 v58, v44
	v_mov_b32_e32 v59, v52
	v_pk_mul_f32 v[58:59], v[148:149], v[58:59] op_sel_hi:[0,1]
	v_mul_f32_e32 v44, 0xbfb8aa3b, v59
	v_exp_f32_e32 v44, v44
	v_mov_b32_e32 v52, v45
	v_add_u32_e32 v56, 0x90, v151
	v_mad_i64_i32 v[56:57], s[42:43], v56, s19, v[158:159]
	v_add_f32_e32 v44, 1.0, v44
	v_rcp_f32_e32 v44, v44
	s_nop 0
	v_mul_f32_e32 v44, v59, v44
	v_mul_f32_e32 v60, v58, v44
	v_mov_b32_e32 v58, v40
	v_mov_b32_e32 v59, v48
	v_pk_mul_f32 v[58:59], v[148:149], v[58:59] op_sel_hi:[0,1]
	v_mul_f32_e32 v40, 0xbfb8aa3b, v59
	v_exp_f32_e32 v40, v40
	v_pk_mul_f32 v[44:45], v[148:149], v[52:53] op_sel_hi:[0,1]
	v_mov_b32_e32 v48, v41
	v_add_f32_e32 v40, 1.0, v40
	v_rcp_f32_e32 v40, v40
	s_nop 0
	v_mul_f32_e32 v40, v59, v40
	v_mul_f32_e32 v58, v58, v40
	v_mul_f32_e32 v40, 0xbfb8aa3b, v45
	v_exp_f32_e32 v40, v40
	s_nop 0
	v_add_f32_e32 v40, 1.0, v40
	v_rcp_f32_e32 v40, v40
	s_nop 0
	v_mul_f32_e32 v40, v45, v40
	v_mul_f32_e32 v52, v44, v40
	v_pk_mul_f32 v[40:41], v[148:149], v[48:49] op_sel_hi:[0,1]
	v_mul_f32_e32 v44, 0xbfb8aa3b, v41
	v_exp_f32_e32 v44, v44
	s_nop 0
	v_add_f32_e32 v44, 1.0, v44
	v_rcp_f32_e32 v44, v44
	s_nop 0
	v_mul_f32_e32 v41, v41, v44
	v_mul_f32_e32 v48, v40, v41
	v_mov_b32_e32 v40, v46
	v_mov_b32_e32 v41, v54
	v_pk_mul_f32 v[40:41], v[148:149], v[40:41] op_sel_hi:[0,1]
	v_mul_f32_e32 v44, 0xbfb8aa3b, v41
	v_exp_f32_e32 v44, v44
	v_mov_b32_e32 v54, v47
	v_add_f32_e32 v44, 1.0, v44
	v_rcp_f32_e32 v44, v44
	s_nop 0
	v_mul_f32_e32 v41, v41, v44
	v_mul_f32_e32 v46, v40, v41
	v_mov_b32_e32 v40, v42
	v_mov_b32_e32 v41, v50
	v_pk_mul_f32 v[40:41], v[148:149], v[40:41] op_sel_hi:[0,1]
	v_mul_f32_e32 v42, 0xbfb8aa3b, v41
	v_exp_f32_e32 v42, v42
	v_mov_b32_e32 v50, v43
	v_lshl_add_u64 v[44:45], v[56:57], 0, v[120:121]
	v_add_f32_e32 v42, 1.0, v42
	v_rcp_f32_e32 v42, v42
	s_nop 0
	v_mul_f32_e32 v41, v41, v42
	v_mul_f32_e32 v49, v40, v41
	v_pk_mul_f32 v[40:41], v[148:149], v[54:55] op_sel_hi:[0,1]
	v_mul_f32_e32 v42, 0xbfb8aa3b, v41
	v_exp_f32_e32 v42, v42
	s_nop 0
	v_add_f32_e32 v42, 1.0, v42
	v_rcp_f32_e32 v42, v42
	s_nop 0
	v_mul_f32_e32 v41, v41, v42
	v_mul_f32_e32 v42, v40, v41
	v_pk_mul_f32 v[40:41], v[148:149], v[50:51] op_sel_hi:[0,1]
	v_mul_f32_e32 v43, 0xbfb8aa3b, v41
	v_exp_f32_e32 v43, v43
	s_nop 0
	v_add_f32_e32 v43, 1.0, v43
	v_rcp_f32_e32 v43, v43
	s_nop 0
	v_mul_f32_e32 v41, v41, v43
	v_mul_f32_e32 v43, v40, v41
	v_cvt_pk_bf16_f32 v40, v60, v52
	v_cvt_pk_bf16_f32 v41, v46, v42
	v_cvt_pk_bf16_f32 v42, v58, v48
	v_cvt_pk_bf16_f32 v43, v49, v43
	global_store_dwordx4 v[44:45], v[40:43], off
	s_nop 1
	v_mov_b32_e32 v42, v26
	v_mov_b32_e32 v43, v36
	v_pk_mul_f32 v[42:43], v[146:147], v[42:43] op_sel_hi:[0,1]
	v_mul_f32_e32 v26, 0xbfb8aa3b, v43
	v_exp_f32_e32 v26, v26
	v_mov_b32_e32 v36, v27
	v_add_u32_e32 v40, 0xa0, v151
	v_mad_i64_i32 v[40:41], s[42:43], v40, s19, v[158:159]
	v_add_f32_e32 v26, 1.0, v26
	v_rcp_f32_e32 v26, v26
	s_nop 0
	v_mul_f32_e32 v26, v43, v26
	v_mul_f32_e32 v44, v42, v26
	v_mov_b32_e32 v42, v22
	v_mov_b32_e32 v43, v30
	v_pk_mul_f32 v[42:43], v[146:147], v[42:43] op_sel_hi:[0,1]
	v_mul_f32_e32 v22, 0xbfb8aa3b, v43
	v_exp_f32_e32 v22, v22
	v_pk_mul_f32 v[26:27], v[146:147], v[36:37] op_sel_hi:[0,1]
	v_mov_b32_e32 v30, v23
	v_add_f32_e32 v22, 1.0, v22
	v_rcp_f32_e32 v22, v22
	s_nop 0
	v_mul_f32_e32 v22, v43, v22
	v_mul_f32_e32 v42, v42, v22
	v_mul_f32_e32 v22, 0xbfb8aa3b, v27
	v_exp_f32_e32 v22, v22
	s_nop 0
	v_add_f32_e32 v22, 1.0, v22
	v_rcp_f32_e32 v22, v22
	s_nop 0
	v_mul_f32_e32 v22, v27, v22
	v_mul_f32_e32 v36, v26, v22
	v_pk_mul_f32 v[22:23], v[146:147], v[30:31] op_sel_hi:[0,1]
	v_mul_f32_e32 v26, 0xbfb8aa3b, v23
	v_exp_f32_e32 v26, v26
	s_nop 0
	v_add_f32_e32 v26, 1.0, v26
	v_rcp_f32_e32 v26, v26
	s_nop 0
	v_mul_f32_e32 v23, v23, v26
	v_mul_f32_e32 v30, v22, v23
	v_mov_b32_e32 v22, v28
	v_mov_b32_e32 v23, v38
	v_pk_mul_f32 v[22:23], v[146:147], v[22:23] op_sel_hi:[0,1]
	v_mul_f32_e32 v26, 0xbfb8aa3b, v23
	v_exp_f32_e32 v26, v26
	v_mov_b32_e32 v38, v29
	v_add_f32_e32 v26, 1.0, v26
	v_rcp_f32_e32 v26, v26
	s_nop 0
	v_mul_f32_e32 v23, v23, v26
	v_mul_f32_e32 v28, v22, v23
	v_mov_b32_e32 v22, v24
	v_mov_b32_e32 v23, v32
	v_pk_mul_f32 v[22:23], v[146:147], v[22:23] op_sel_hi:[0,1]
	v_mul_f32_e32 v24, 0xbfb8aa3b, v23
	v_exp_f32_e32 v24, v24
	v_mov_b32_e32 v32, v25
	v_lshl_add_u64 v[26:27], v[40:41], 0, v[120:121]
	v_add_f32_e32 v24, 1.0, v24
	v_rcp_f32_e32 v24, v24
	s_nop 0
	v_mul_f32_e32 v23, v23, v24
	v_mul_f32_e32 v31, v22, v23
	v_pk_mul_f32 v[22:23], v[146:147], v[38:39] op_sel_hi:[0,1]
	v_mul_f32_e32 v24, 0xbfb8aa3b, v23
	v_exp_f32_e32 v24, v24
	s_nop 0
	v_add_f32_e32 v24, 1.0, v24
	v_rcp_f32_e32 v24, v24
	s_nop 0
	v_mul_f32_e32 v23, v23, v24
	v_mul_f32_e32 v24, v22, v23
	v_pk_mul_f32 v[22:23], v[146:147], v[32:33] op_sel_hi:[0,1]
	v_mul_f32_e32 v25, 0xbfb8aa3b, v23
	v_exp_f32_e32 v25, v25
	s_nop 0
	v_add_f32_e32 v25, 1.0, v25
	v_rcp_f32_e32 v25, v25
	s_nop 0
	v_mul_f32_e32 v23, v23, v25
	v_mul_f32_e32 v25, v22, v23
	v_cvt_pk_bf16_f32 v22, v44, v36
	v_cvt_pk_bf16_f32 v23, v28, v24
	v_cvt_pk_bf16_f32 v24, v42, v30
	v_cvt_pk_bf16_f32 v25, v31, v25
	global_store_dwordx4 v[26:27], v[22:25], off
	s_nop 1
	v_mov_b32_e32 v24, v6
	v_mov_b32_e32 v25, v18
	v_pk_mul_f32 v[24:25], v[140:141], v[24:25] op_sel_hi:[0,1]
	v_mul_f32_e32 v6, 0xbfb8aa3b, v25
	v_exp_f32_e32 v6, v6
	v_mov_b32_e32 v18, v7
	v_add_u32_e32 v22, 0xb0, v151
	v_mad_i64_i32 v[22:23], s[42:43], v22, s19, v[158:159]
	v_add_f32_e32 v6, 1.0, v6
	v_rcp_f32_e32 v6, v6
	s_mov_b64 s[42:43], -1
	v_mul_f32_e32 v6, v25, v6
	v_mul_f32_e32 v26, v24, v6
	v_mov_b32_e32 v24, v2
	v_mov_b32_e32 v25, v10
	v_pk_mul_f32 v[24:25], v[140:141], v[24:25] op_sel_hi:[0,1]
	v_mul_f32_e32 v2, 0xbfb8aa3b, v25
	v_exp_f32_e32 v2, v2
	v_pk_mul_f32 v[6:7], v[140:141], v[18:19] op_sel_hi:[0,1]
	v_mov_b32_e32 v10, v3
	v_add_f32_e32 v2, 1.0, v2
	v_rcp_f32_e32 v2, v2
	s_nop 0
	v_mul_f32_e32 v2, v25, v2
	v_mul_f32_e32 v24, v24, v2
	v_mul_f32_e32 v2, 0xbfb8aa3b, v7
	v_exp_f32_e32 v2, v2
	s_nop 0
	v_add_f32_e32 v2, 1.0, v2
	v_rcp_f32_e32 v2, v2
	s_nop 0
	v_mul_f32_e32 v2, v7, v2
	v_mul_f32_e32 v18, v6, v2
	v_pk_mul_f32 v[2:3], v[140:141], v[10:11] op_sel_hi:[0,1]
	v_mul_f32_e32 v6, 0xbfb8aa3b, v3
	v_exp_f32_e32 v6, v6
	s_nop 0
	v_add_f32_e32 v6, 1.0, v6
	v_rcp_f32_e32 v6, v6
	s_nop 0
	v_mul_f32_e32 v3, v3, v6
	v_mul_f32_e32 v10, v2, v3
	v_mov_b32_e32 v2, v8
	v_mov_b32_e32 v3, v20
	v_pk_mul_f32 v[2:3], v[140:141], v[2:3] op_sel_hi:[0,1]
	v_mul_f32_e32 v6, 0xbfb8aa3b, v3
	v_exp_f32_e32 v6, v6
	v_mov_b32_e32 v20, v9
	v_add_f32_e32 v6, 1.0, v6
	v_rcp_f32_e32 v6, v6
	s_nop 0
	v_mul_f32_e32 v3, v3, v6
	v_mul_f32_e32 v8, v2, v3
	v_mov_b32_e32 v2, v4
	v_mov_b32_e32 v3, v12
	v_pk_mul_f32 v[2:3], v[140:141], v[2:3] op_sel_hi:[0,1]
	v_mul_f32_e32 v4, 0xbfb8aa3b, v3
	v_exp_f32_e32 v4, v4
	v_mov_b32_e32 v12, v5
	v_lshl_add_u64 v[6:7], v[22:23], 0, v[120:121]
	v_add_f32_e32 v4, 1.0, v4
	v_rcp_f32_e32 v4, v4
	s_nop 0
	v_mul_f32_e32 v3, v3, v4
	v_mul_f32_e32 v11, v2, v3
	v_pk_mul_f32 v[2:3], v[140:141], v[20:21] op_sel_hi:[0,1]
	v_mul_f32_e32 v4, 0xbfb8aa3b, v3
	v_exp_f32_e32 v4, v4
	s_nop 0
	v_add_f32_e32 v4, 1.0, v4
	v_rcp_f32_e32 v4, v4
	s_nop 0
	v_mul_f32_e32 v3, v3, v4
	v_mul_f32_e32 v4, v2, v3
	v_pk_mul_f32 v[2:3], v[140:141], v[12:13] op_sel_hi:[0,1]
	v_mul_f32_e32 v5, 0xbfb8aa3b, v3
	v_exp_f32_e32 v5, v5
	s_nop 0
	v_add_f32_e32 v5, 1.0, v5
	v_rcp_f32_e32 v5, v5
	s_nop 0
	v_mul_f32_e32 v3, v3, v5
	v_mul_f32_e32 v5, v2, v3
	v_cvt_pk_bf16_f32 v2, v26, v18
	v_cvt_pk_bf16_f32 v3, v8, v4
	v_cvt_pk_bf16_f32 v4, v24, v10
	v_cvt_pk_bf16_f32 v5, v11, v5
	global_store_dwordx4 v[6:7], v[2:5], off
	s_cbranch_vccnz .LBB0_1660
	s_nop 0
	v_lshl_add_u32 v2, s28, 8, v17
	v_ashrrev_i32_e32 v3, 31, v2
	v_lshl_add_u64 v[2:3], v[2:3], 2, s[0:1]
	global_load_dword v160, v[2:3], off
	global_load_dword v156, v[2:3], off offset:64
	global_load_dword v154, v[2:3], off offset:128
	global_load_dword v152, v[2:3], off offset:192
	global_load_dword v150, v[2:3], off offset:512
	global_load_dword v148, v[2:3], off offset:576
	global_load_dword v146, v[2:3], off offset:640
	global_load_dword v140, v[2:3], off offset:704
	s_andn2_b64 vcc, exec, s[4:5]
	s_cbranch_vccnz .LBB0_1659
	s_barrier
	s_branch .LBB0_1659
